# P6 K-loop: second super-phase A fragments read during the first super-phase MFMA block (into spare VGPRs)
# baseline (speedup 1.0000x reference)
.LBB0_1371:
	v_add_u32_e32 v147, s64, v143
	v_add_u32_e32 v152, s64, v144
	ds_read_b128 v[148:151], v147
	ds_read_b128 v[152:155], v152
	v_add_u32_e32 v147, s65, v143
	v_add_u32_e32 v162, s65, v144
	s_add_u32 s58, s18, s56
	ds_read_b128 v[158:161], v147
	ds_read_b128 v[162:165], v162
	v_add_u32_e32 v147, s66, v143
	s_addc_u32 s59, s19, s57
	v_add_u32_e32 v166, s66, v144
	ds_read_b128 v[170:173], v147
	ds_read_b128 v[174:177], v166
	v_add_u32_e32 v147, s67, v143
	s_add_u32 s58, s58, 0x100
	v_add_u32_e32 v166, s67, v144
	ds_read_b128 v[178:181], v147
	ds_read_b128 v[182:185], v166
	s_addc_u32 s59, s59, 0
	s_add_u32 s78, s53, s56
	s_addc_u32 s79, s72, s57
	s_cmpk_eq_i32 s56, 0x1f00
	s_cselect_b32 s79, s49, s79
	s_cselect_b32 s78, s76, s78
	s_cselect_b32 s59, s51, s59
	s_cselect_b32 s58, s73, s58
	v_lshl_add_u64 v[166:167], v[140:141], 0, s[56:57]
	v_lshl_add_u64 v[218:219], v[166:167], 0, s[24:25]
	s_add_i32 m0, s35, 0x8000
	ds_read_b128 v[186:189], v145
	ds_read_b128 v[190:193], v145 offset:2048
	ds_read_b128 v[194:197], v146
	ds_read_b128 v[198:201], v146 offset:2048
	ds_read_b128 v[202:205], v145 offset:4096
	ds_read_b128 v[206:209], v145 offset:6144
	ds_read_b128 v[210:213], v146 offset:4096
	ds_read_b128 v[214:217], v146 offset:6144
	global_load_lds_dwordx4 v[218:219], off
	v_lshl_add_u64 v[218:219], v[166:167], 0, s[44:45]
	s_add_i32 m0, s35, 0xa000
	s_nop 0
	global_load_lds_dwordx4 v[218:219], off
	v_lshl_add_u64 v[218:219], v[166:167], 0, s[28:29]
	s_add_i32 m0, s35, 0xc000
	v_lshl_add_u64 v[166:167], v[166:167], 0, s[46:47]
	global_load_lds_dwordx4 v[218:219], off
	s_add_i32 m0, s35, 0xe000
	s_nop 0
	global_load_lds_dwordx4 v[166:167], off
	s_waitcnt vmcnt(8)
	s_waitcnt lgkmcnt(0)
	s_barrier
	v_mfma_f32_16x16x32_bf16 v[128:131], v[148:151], v[186:189], v[128:131]
	v_mfma_f32_16x16x32_bf16 v[128:131], v[152:155], v[194:197], v[128:131]
	v_mfma_f32_16x16x32_bf16 v[112:115], v[152:155], v[198:201], v[112:115]
	v_mfma_f32_16x16x32_bf16 v[112:115], v[148:151], v[190:193], v[112:115]
	v_mfma_f32_16x16x32_bf16 v[96:99], v[148:151], v[202:205], v[96:99]
	v_mfma_f32_16x16x32_bf16 v[96:99], v[152:155], v[210:213], v[96:99]
	v_mfma_f32_16x16x32_bf16 v[80:83], v[152:155], v[214:217], v[80:83]
	v_mfma_f32_16x16x32_bf16 v[80:83], v[148:151], v[206:209], v[80:83]
	v_mfma_f32_16x16x32_bf16 v[76:79], v[158:161], v[206:209], v[76:79]
	ds_read_b128 v[222:225], v145 offset:16384
	v_mfma_f32_16x16x32_bf16 v[76:79], v[162:165], v[214:217], v[76:79]
	v_mfma_f32_16x16x32_bf16 v[92:95], v[162:165], v[210:213], v[92:95]
	ds_read_b128 v[226:229], v145 offset:18432
	v_mfma_f32_16x16x32_bf16 v[92:95], v[158:161], v[202:205], v[92:95]
	v_mfma_f32_16x16x32_bf16 v[108:111], v[158:161], v[190:193], v[108:111]
	ds_read_b128 v[230:233], v146 offset:16384
	v_mfma_f32_16x16x32_bf16 v[108:111], v[162:165], v[198:201], v[108:111]
	v_mfma_f32_16x16x32_bf16 v[124:127], v[162:165], v[194:197], v[124:127]
	ds_read_b128 v[234:237], v146 offset:18432
	v_mfma_f32_16x16x32_bf16 v[124:127], v[158:161], v[186:189], v[124:127]
	v_mfma_f32_16x16x32_bf16 v[120:123], v[170:173], v[186:189], v[120:123]
	ds_read_b128 v[238:241], v145 offset:20480
	v_mfma_f32_16x16x32_bf16 v[120:123], v[174:177], v[194:197], v[120:123]
	v_mfma_f32_16x16x32_bf16 v[104:107], v[174:177], v[198:201], v[104:107]
	ds_read_b128 v[242:245], v145 offset:22528
	v_mfma_f32_16x16x32_bf16 v[104:107], v[170:173], v[190:193], v[104:107]
	v_mfma_f32_16x16x32_bf16 v[88:91], v[170:173], v[202:205], v[88:91]
	ds_read_b128 v[246:249], v146 offset:20480
	v_mfma_f32_16x16x32_bf16 v[88:91], v[174:177], v[210:213], v[88:91]
	v_mfma_f32_16x16x32_bf16 v[72:75], v[174:177], v[214:217], v[72:75]
	ds_read_b128 v[250:253], v146 offset:22528
	v_mfma_f32_16x16x32_bf16 v[72:75], v[170:173], v[206:209], v[72:75]
	v_mfma_f32_16x16x32_bf16 v[68:71], v[178:181], v[206:209], v[68:71]
	v_mfma_f32_16x16x32_bf16 v[68:71], v[182:185], v[214:217], v[68:71]
	v_mfma_f32_16x16x32_bf16 v[84:87], v[182:185], v[210:213], v[84:87]
	v_mfma_f32_16x16x32_bf16 v[84:87], v[178:181], v[202:205], v[84:87]
	v_mfma_f32_16x16x32_bf16 v[100:103], v[178:181], v[190:193], v[100:103]
	v_mfma_f32_16x16x32_bf16 v[100:103], v[182:185], v[198:201], v[100:103]
	v_mfma_f32_16x16x32_bf16 v[116:119], v[182:185], v[194:197], v[116:119]
	v_mfma_f32_16x16x32_bf16 v[116:119], v[178:181], v[186:189], v[116:119]
	s_barrier
	v_lshl_add_u64 v[166:167], s[78:79], 0, v[132:133]
	s_add_i32 s78, s64, s34
	s_mov_b32 m0, s78
	global_load_lds_dwordx4 v[166:167], off
	v_lshl_add_u64 v[218:219], v[166:167], 0, s[10:11]
	s_add_i32 m0, s78, 0x2000
	s_add_i32 s78, s66, s34
	global_load_lds_dwordx4 v[218:219], off
	v_lshl_add_u64 v[218:219], v[166:167], 0, s[14:15]
	s_mov_b32 m0, s78
	s_nop 0
	global_load_lds_dwordx4 v[218:219], off
	v_lshl_add_u64 v[218:219], v[166:167], 0, s[16:17]
	s_add_i32 m0, s78, 0x2000
	s_nop 0
	global_load_lds_dwordx4 v[218:219], off
	s_waitcnt vmcnt(4)
	s_waitcnt lgkmcnt(0)
	s_barrier
	v_mfma_f32_16x16x32_bf16 v[64:67], v[148:151], v[222:225], v[64:67]
	v_mfma_f32_16x16x32_bf16 v[64:67], v[152:155], v[230:233], v[64:67]
	v_mfma_f32_16x16x32_bf16 v[48:51], v[152:155], v[234:237], v[48:51]
	v_mfma_f32_16x16x32_bf16 v[48:51], v[148:151], v[226:229], v[48:51]
	v_mfma_f32_16x16x32_bf16 v[32:35], v[148:151], v[238:241], v[32:35]
	v_mfma_f32_16x16x32_bf16 v[32:35], v[152:155], v[246:249], v[32:35]
	v_mfma_f32_16x16x32_bf16 v[16:19], v[152:155], v[250:253], v[16:19]
	v_mfma_f32_16x16x32_bf16 v[16:19], v[148:151], v[242:245], v[16:19]
	v_mfma_f32_16x16x32_bf16 v[12:15], v[158:161], v[242:245], v[12:15]
	v_mfma_f32_16x16x32_bf16 v[12:15], v[162:165], v[250:253], v[12:15]
	v_mfma_f32_16x16x32_bf16 v[28:31], v[162:165], v[246:249], v[28:31]
	v_mfma_f32_16x16x32_bf16 v[28:31], v[158:161], v[238:241], v[28:31]
	v_mfma_f32_16x16x32_bf16 v[44:47], v[158:161], v[226:229], v[44:47]
	v_mfma_f32_16x16x32_bf16 v[44:47], v[162:165], v[234:237], v[44:47]
	v_mfma_f32_16x16x32_bf16 v[60:63], v[162:165], v[230:233], v[60:63]
	v_mfma_f32_16x16x32_bf16 v[60:63], v[158:161], v[222:225], v[60:63]
	v_mfma_f32_16x16x32_bf16 v[56:59], v[170:173], v[222:225], v[56:59]
	v_mfma_f32_16x16x32_bf16 v[56:59], v[174:177], v[230:233], v[56:59]
	v_mfma_f32_16x16x32_bf16 v[40:43], v[174:177], v[234:237], v[40:43]
	v_mfma_f32_16x16x32_bf16 v[40:43], v[170:173], v[226:229], v[40:43]
	v_mfma_f32_16x16x32_bf16 v[24:27], v[170:173], v[238:241], v[24:27]
	v_mfma_f32_16x16x32_bf16 v[24:27], v[174:177], v[246:249], v[24:27]
	v_mfma_f32_16x16x32_bf16 v[8:11], v[174:177], v[250:253], v[8:11]
	v_mfma_f32_16x16x32_bf16 v[8:11], v[170:173], v[242:245], v[8:11]
	v_mfma_f32_16x16x32_bf16 v[4:7], v[178:181], v[242:245], v[4:7]
	v_mfma_f32_16x16x32_bf16 v[4:7], v[182:185], v[250:253], v[4:7]
	v_mfma_f32_16x16x32_bf16 v[20:23], v[182:185], v[246:249], v[20:23]
	v_mfma_f32_16x16x32_bf16 v[20:23], v[178:181], v[238:241], v[20:23]
	v_mfma_f32_16x16x32_bf16 v[36:39], v[178:181], v[226:229], v[36:39]
	v_mfma_f32_16x16x32_bf16 v[36:39], v[182:185], v[234:237], v[36:39]
	v_mfma_f32_16x16x32_bf16 v[52:55], v[182:185], v[230:233], v[52:55]
	v_mfma_f32_16x16x32_bf16 v[52:55], v[178:181], v[222:225], v[52:55]
	s_barrier
	v_add_u32_e32 v147, s70, v143
	v_add_u32_e32 v152, s70, v144
	ds_read_b128 v[148:151], v147
	ds_read_b128 v[152:155], v152
	v_add_u32_e32 v147, s68, v143
	v_add_u32_e32 v162, s68, v144
	ds_read_b128 v[158:161], v147
	ds_read_b128 v[162:165], v162
	v_add_u32_e32 v147, s71, v143
	v_add_u32_e32 v169, s71, v144
	ds_read_b128 v[170:173], v147
	ds_read_b128 v[174:177], v169
	v_add_u32_e32 v147, s69, v143
	v_add_u32_e32 v169, s69, v144
	ds_read_b128 v[178:181], v147
	ds_read_b128 v[182:185], v169
	s_mov_b32 m0, s35
	v_lshl_add_u64 v[218:219], s[58:59], 0, v[0:1]
	ds_read_b128 v[186:189], v145 offset:32768
	ds_read_b128 v[190:193], v145 offset:34816
	ds_read_b128 v[194:197], v146 offset:32768
	ds_read_b128 v[198:201], v146 offset:34816
	ds_read_b128 v[202:205], v145 offset:36864
	ds_read_b128 v[206:209], v145 offset:38912
	ds_read_b128 v[210:213], v146 offset:36864
	ds_read_b128 v[214:217], v146 offset:38912
	global_load_lds_dwordx4 v[218:219], off
	v_lshl_add_u64 v[220:221], v[218:219], 0, s[20:21]
	s_mov_b32 m0, s39
	s_nop 0
	global_load_lds_dwordx4 v[220:221], off
	v_lshl_add_u64 v[220:221], v[218:219], 0, s[10:11]
	s_mov_b32 m0, s60
	v_lshl_add_u64 v[218:219], v[218:219], 0, s[22:23]
	global_load_lds_dwordx4 v[220:221], off
	s_mov_b32 m0, s61
	s_nop 0
	global_load_lds_dwordx4 v[218:219], off
	s_waitcnt vmcnt(8)
	s_waitcnt lgkmcnt(0)
	s_barrier
	v_mfma_f32_16x16x32_bf16 v[128:131], v[148:151], v[186:189], v[128:131]
	v_mfma_f32_16x16x32_bf16 v[128:131], v[152:155], v[194:197], v[128:131]
	v_mfma_f32_16x16x32_bf16 v[112:115], v[152:155], v[198:201], v[112:115]
	v_mfma_f32_16x16x32_bf16 v[112:115], v[148:151], v[190:193], v[112:115]
	v_mfma_f32_16x16x32_bf16 v[96:99], v[148:151], v[202:205], v[96:99]
	v_mfma_f32_16x16x32_bf16 v[96:99], v[152:155], v[210:213], v[96:99]
	v_mfma_f32_16x16x32_bf16 v[80:83], v[152:155], v[214:217], v[80:83]
	v_mfma_f32_16x16x32_bf16 v[80:83], v[148:151], v[206:209], v[80:83]
	v_mfma_f32_16x16x32_bf16 v[76:79], v[158:161], v[206:209], v[76:79]
	ds_read_b128 v[222:225], v145 offset:49152
	v_mfma_f32_16x16x32_bf16 v[76:79], v[162:165], v[214:217], v[76:79]
	v_mfma_f32_16x16x32_bf16 v[92:95], v[162:165], v[210:213], v[92:95]
	ds_read_b128 v[226:229], v145 offset:51200
	v_mfma_f32_16x16x32_bf16 v[92:95], v[158:161], v[202:205], v[92:95]
	v_mfma_f32_16x16x32_bf16 v[108:111], v[158:161], v[190:193], v[108:111]
	ds_read_b128 v[230:233], v146 offset:49152
	v_mfma_f32_16x16x32_bf16 v[108:111], v[162:165], v[198:201], v[108:111]
	v_mfma_f32_16x16x32_bf16 v[124:127], v[162:165], v[194:197], v[124:127]
	ds_read_b128 v[234:237], v146 offset:51200
	v_mfma_f32_16x16x32_bf16 v[124:127], v[158:161], v[186:189], v[124:127]
	v_mfma_f32_16x16x32_bf16 v[120:123], v[170:173], v[186:189], v[120:123]
	ds_read_b128 v[238:241], v145 offset:53248
	v_mfma_f32_16x16x32_bf16 v[120:123], v[174:177], v[194:197], v[120:123]
	v_mfma_f32_16x16x32_bf16 v[104:107], v[174:177], v[198:201], v[104:107]
	ds_read_b128 v[242:245], v145 offset:55296
	v_mfma_f32_16x16x32_bf16 v[104:107], v[170:173], v[190:193], v[104:107]
	v_mfma_f32_16x16x32_bf16 v[88:91], v[170:173], v[202:205], v[88:91]
	ds_read_b128 v[246:249], v146 offset:53248
	v_mfma_f32_16x16x32_bf16 v[88:91], v[174:177], v[210:213], v[88:91]
	v_mfma_f32_16x16x32_bf16 v[72:75], v[174:177], v[214:217], v[72:75]
	ds_read_b128 v[250:253], v146 offset:55296
	v_mfma_f32_16x16x32_bf16 v[72:75], v[170:173], v[206:209], v[72:75]
	v_mfma_f32_16x16x32_bf16 v[68:71], v[178:181], v[206:209], v[68:71]
	v_mfma_f32_16x16x32_bf16 v[68:71], v[182:185], v[214:217], v[68:71]
	v_mfma_f32_16x16x32_bf16 v[84:87], v[182:185], v[210:213], v[84:87]
	v_mfma_f32_16x16x32_bf16 v[84:87], v[178:181], v[202:205], v[84:87]
	v_mfma_f32_16x16x32_bf16 v[100:103], v[178:181], v[190:193], v[100:103]
	v_mfma_f32_16x16x32_bf16 v[100:103], v[182:185], v[198:201], v[100:103]
	v_mfma_f32_16x16x32_bf16 v[116:119], v[182:185], v[194:197], v[116:119]
	v_mfma_f32_16x16x32_bf16 v[116:119], v[178:181], v[186:189], v[116:119]
	s_barrier
	s_add_i32 s58, s70, s34
	v_lshl_add_u64 v[218:219], v[166:167], 0, s[24:25]
	s_mov_b32 m0, s58
	global_load_lds_dwordx4 v[218:219], off
	v_lshl_add_u64 v[218:219], v[166:167], 0, s[28:29]
	s_add_i32 m0, s58, 0x2000
	s_add_i32 s58, s71, s34
	global_load_lds_dwordx4 v[218:219], off
	v_lshl_add_u64 v[218:219], v[166:167], 0, s[36:37]
	s_mov_b32 m0, s58
	v_lshl_add_u64 v[166:167], v[166:167], 0, s[40:41]
	global_load_lds_dwordx4 v[218:219], off
	s_add_i32 m0, s58, 0x2000
	s_nop 0
	global_load_lds_dwordx4 v[166:167], off
	s_waitcnt vmcnt(4)
	s_waitcnt lgkmcnt(0)
	s_barrier
	v_mfma_f32_16x16x32_bf16 v[64:67], v[148:151], v[222:225], v[64:67]
	v_mfma_f32_16x16x32_bf16 v[64:67], v[152:155], v[230:233], v[64:67]
	v_mfma_f32_16x16x32_bf16 v[48:51], v[152:155], v[234:237], v[48:51]
	v_mfma_f32_16x16x32_bf16 v[48:51], v[148:151], v[226:229], v[48:51]
	v_mfma_f32_16x16x32_bf16 v[32:35], v[148:151], v[238:241], v[32:35]
	v_mfma_f32_16x16x32_bf16 v[32:35], v[152:155], v[246:249], v[32:35]
	v_mfma_f32_16x16x32_bf16 v[16:19], v[152:155], v[250:253], v[16:19]
	v_mfma_f32_16x16x32_bf16 v[16:19], v[148:151], v[242:245], v[16:19]
	v_mfma_f32_16x16x32_bf16 v[12:15], v[158:161], v[242:245], v[12:15]
	v_mfma_f32_16x16x32_bf16 v[12:15], v[162:165], v[250:253], v[12:15]
	v_mfma_f32_16x16x32_bf16 v[28:31], v[162:165], v[246:249], v[28:31]
	v_mfma_f32_16x16x32_bf16 v[28:31], v[158:161], v[238:241], v[28:31]
	v_mfma_f32_16x16x32_bf16 v[44:47], v[158:161], v[226:229], v[44:47]
	v_mfma_f32_16x16x32_bf16 v[44:47], v[162:165], v[234:237], v[44:47]
	v_mfma_f32_16x16x32_bf16 v[60:63], v[162:165], v[230:233], v[60:63]
	v_mfma_f32_16x16x32_bf16 v[60:63], v[158:161], v[222:225], v[60:63]
	v_mfma_f32_16x16x32_bf16 v[56:59], v[170:173], v[222:225], v[56:59]
	v_mfma_f32_16x16x32_bf16 v[56:59], v[174:177], v[230:233], v[56:59]
	v_mfma_f32_16x16x32_bf16 v[40:43], v[174:177], v[234:237], v[40:43]
	v_mfma_f32_16x16x32_bf16 v[40:43], v[170:173], v[226:229], v[40:43]
	v_mfma_f32_16x16x32_bf16 v[24:27], v[170:173], v[238:241], v[24:27]
	v_mfma_f32_16x16x32_bf16 v[24:27], v[174:177], v[246:249], v[24:27]
	v_mfma_f32_16x16x32_bf16 v[8:11], v[174:177], v[250:253], v[8:11]
	v_mfma_f32_16x16x32_bf16 v[8:11], v[170:173], v[242:245], v[8:11]
	v_mfma_f32_16x16x32_bf16 v[4:7], v[178:181], v[242:245], v[4:7]
	v_mfma_f32_16x16x32_bf16 v[4:7], v[182:185], v[250:253], v[4:7]
	v_mfma_f32_16x16x32_bf16 v[20:23], v[182:185], v[246:249], v[20:23]
	v_mfma_f32_16x16x32_bf16 v[20:23], v[178:181], v[238:241], v[20:23]
	v_mfma_f32_16x16x32_bf16 v[36:39], v[178:181], v[226:229], v[36:39]
	v_mfma_f32_16x16x32_bf16 v[36:39], v[182:185], v[234:237], v[36:39]
	v_mfma_f32_16x16x32_bf16 v[52:55], v[182:185], v[230:233], v[52:55]
	v_mfma_f32_16x16x32_bf16 v[52:55], v[178:181], v[222:225], v[52:55]
	s_barrier
	s_add_i32 s77, s77, 2
	s_add_u32 s56, s56, 0x100
	s_addc_u32 s57, s57, 0
	s_cmp_gt_u32 s77, 61
	s_cbranch_scc0 .LBB0_1371
	s_add_u32 s56, s53, 0xffffff00
	s_addc_u32 s57, s72, -1
	s_andn2_b64 vcc, exec, s[6:7]
	s_cbranch_vccnz .LBB0_1362
	v_mov_b32_e32 v4, 0
	s_mov_b32 s0, s48
	s_mov_b32 s8, s50
	s_mov_b64 s[18:19], s[54:55]
	s_mov_b32 s63, s52
	v_mov_b32_e32 v5, v4
	v_mov_b32_e32 v6, v4
	v_mov_b32_e32 v7, v4
	v_mov_b32_e32 v8, v4
	v_mov_b32_e32 v9, v4
	v_mov_b32_e32 v10, v4
	v_mov_b32_e32 v11, v4
	v_mov_b32_e32 v20, v4
	v_mov_b32_e32 v21, v4
	v_mov_b32_e32 v22, v4
	v_mov_b32_e32 v23, v4
	v_mov_b32_e32 v24, v4
	v_mov_b32_e32 v25, v4
	v_mov_b32_e32 v26, v4
	v_mov_b32_e32 v27, v4
	v_mov_b32_e32 v36, v4
	v_mov_b32_e32 v37, v4
	v_mov_b32_e32 v38, v4
	v_mov_b32_e32 v39, v4
	v_mov_b32_e32 v40, v4
	v_mov_b32_e32 v41, v4
	v_mov_b32_e32 v42, v4
	v_mov_b32_e32 v43, v4
	v_mov_b32_e32 v52, v4
	v_mov_b32_e32 v53, v4
	v_mov_b32_e32 v54, v4
	v_mov_b32_e32 v55, v4
	v_mov_b32_e32 v56, v4
	v_mov_b32_e32 v57, v4
	v_mov_b32_e32 v58, v4
	v_mov_b32_e32 v59, v4
	v_mov_b32_e32 v12, v4
	v_mov_b32_e32 v13, v4
	v_mov_b32_e32 v14, v4
	v_mov_b32_e32 v15, v4
	v_mov_b32_e32 v16, v4
	v_mov_b32_e32 v17, v4
	v_mov_b32_e32 v18, v4
	v_mov_b32_e32 v19, v4
	v_mov_b32_e32 v28, v4
	v_mov_b32_e32 v29, v4
	v_mov_b32_e32 v30, v4
	v_mov_b32_e32 v31, v4
	v_mov_b32_e32 v32, v4
	v_mov_b32_e32 v33, v4
	v_mov_b32_e32 v34, v4
	v_mov_b32_e32 v35, v4
	v_mov_b32_e32 v44, v4
	v_mov_b32_e32 v45, v4
	v_mov_b32_e32 v46, v4
	v_mov_b32_e32 v47, v4
	v_mov_b32_e32 v48, v4
	v_mov_b32_e32 v49, v4
	v_mov_b32_e32 v50, v4
	v_mov_b32_e32 v51, v4
	v_mov_b32_e32 v60, v4
	v_mov_b32_e32 v61, v4
	v_mov_b32_e32 v62, v4
	v_mov_b32_e32 v63, v4
	v_mov_b32_e32 v64, v4
	v_mov_b32_e32 v65, v4
	v_mov_b32_e32 v66, v4
	v_mov_b32_e32 v67, v4
	v_mov_b32_e32 v68, v4
	v_mov_b32_e32 v69, v4
	v_mov_b32_e32 v70, v4
	v_mov_b32_e32 v71, v4
	v_mov_b32_e32 v72, v4
	v_mov_b32_e32 v73, v4
	v_mov_b32_e32 v74, v4
	v_mov_b32_e32 v75, v4
	v_mov_b32_e32 v84, v4
	v_mov_b32_e32 v85, v4
	v_mov_b32_e32 v86, v4
	v_mov_b32_e32 v87, v4
	v_mov_b32_e32 v88, v4
	v_mov_b32_e32 v89, v4
	v_mov_b32_e32 v90, v4
	v_mov_b32_e32 v91, v4
	v_mov_b32_e32 v100, v4
	v_mov_b32_e32 v101, v4
	v_mov_b32_e32 v102, v4
	v_mov_b32_e32 v103, v4
	v_mov_b32_e32 v104, v4
	v_mov_b32_e32 v105, v4
	v_mov_b32_e32 v106, v4
	v_mov_b32_e32 v107, v4
	v_mov_b32_e32 v116, v4
	v_mov_b32_e32 v117, v4
	v_mov_b32_e32 v118, v4
	v_mov_b32_e32 v119, v4
	v_mov_b32_e32 v120, v4
	v_mov_b32_e32 v121, v4
	v_mov_b32_e32 v122, v4
	v_mov_b32_e32 v123, v4
	v_mov_b32_e32 v76, v4
	v_mov_b32_e32 v77, v4
	v_mov_b32_e32 v78, v4
	v_mov_b32_e32 v79, v4
	v_mov_b32_e32 v80, v4
	v_mov_b32_e32 v81, v4
	v_mov_b32_e32 v82, v4
	v_mov_b32_e32 v83, v4
	v_mov_b32_e32 v92, v4
	v_mov_b32_e32 v93, v4
	v_mov_b32_e32 v94, v4
	v_mov_b32_e32 v95, v4
	v_mov_b32_e32 v96, v4
	v_mov_b32_e32 v97, v4
	v_mov_b32_e32 v98, v4
	v_mov_b32_e32 v99, v4
	v_mov_b32_e32 v108, v4
	v_mov_b32_e32 v109, v4
	v_mov_b32_e32 v110, v4
	v_mov_b32_e32 v111, v4
	v_mov_b32_e32 v112, v4
	v_mov_b32_e32 v113, v4
	v_mov_b32_e32 v114, v4
	v_mov_b32_e32 v115, v4
	v_mov_b32_e32 v124, v4
	v_mov_b32_e32 v125, v4
	v_mov_b32_e32 v126, v4
	v_mov_b32_e32 v127, v4
	v_mov_b32_e32 v128, v4
	v_mov_b32_e32 v129, v4
	v_mov_b32_e32 v130, v4
	v_mov_b32_e32 v131, v4
	s_andn2_b64 vcc, exec, s[4:5]
	s_cbranch_vccnz .LBB0_1363
